# coarser barrier poll back-off (s_sleep 8) stacked on v56
# speedup vs baseline: 1.0056x; 1.0003x over previous
.LBB0_134:
	s_and_b32 s2, s0, 0xff
	s_mov_b64 s[36:37], -1
	s_cmp_lg_u32 s2, 0
	s_mov_b64 s[42:43], -1
	s_sleep 8
	s_cbranch_scc1 .LBB0_137
	v_readlane_b32 s14, v251, 4
	v_readlane_b32 s15, v251, 5
	s_nop 4
	global_load_dword v2, v1, s[14:15] sc1
	s_waitcnt vmcnt(0)
	v_cmp_eq_u32_e32 vcc, 0, v2
	s_cbranch_vccnz .LBB0_139
	s_mov_b64 s[42:43], 0
	s_mov_b64 s[38:39], -1

.LBB0_520:
	s_and_b32 s2, s0, 0xff
	s_mov_b64 s[36:37], -1
	s_cmp_lg_u32 s2, 0
	s_mov_b64 s[44:45], -1
	s_sleep 8
	s_cbranch_scc1 .LBB0_523
	v_readlane_b32 s14, v251, 4
	v_readlane_b32 s15, v251, 5
	s_nop 4
	global_load_dword v2, v1, s[14:15] sc1
	s_waitcnt vmcnt(0)
	v_cmp_eq_u32_e32 vcc, 0, v2
	s_cbranch_vccnz .LBB0_525
	s_mov_b64 s[44:45], 0
	s_mov_b64 s[38:39], -1
